# counted vmcnt at GLA/SSD pass-B chunk tops (do not wait for the previous chunk's store acks) + next-chunk q/k register prefetch in GLA pass B
# baseline (speedup 1.0000x reference)
.LBB0_662:
	s_add_i32 s42, s54, s72
	s_cmpk_lt_i32 s42, 0x100
	s_cselect_b32 s76, 64, 16
	s_cselect_b32 s73, s55, s51
	v_cmp_gt_i32_e32 vcc, s76, v189
	v_mov_b32_e32 v68, 0
	v_mov_b32_e32 v70, 0
	v_mov_b32_e32 v71, 0
	v_mov_b32_e32 v72, 0
	v_mov_b32_e32 v73, 0
	v_mov_b32_e32 v74, 0
	v_mov_b32_e32 v75, 0
	v_mov_b32_e32 v76, 0
	v_mov_b32_e32 v77, 0
	s_waitcnt vmcnt(63) expcnt(7) lgkmcnt(15)
	s_barrier
	s_cmp_eq_u32 s72, 0
	s_cbranch_scc1 .Lgw_0_a
	s_waitcnt vmcnt(20)
	s_branch .Lgw_0_b
.Lgw_0_a:
	s_waitcnt vmcnt(2)
.Lgw_0_b:
	ds_write_b128 v198, v[36:39]
	ds_write_b128 v199, v[40:43]
	ds_write_b128 v200, v[44:47]
	ds_write_b128 v201, v[48:51]
	ds_write_b128 v198, v[52:55] offset:18432
	ds_write_b128 v199, v[64:67] offset:18432
	s_cmp_eq_u32 s72, 0
	s_cbranch_scc1 .Lqkpf_orig_10107
	ds_write_b128 v152, v[224:227] offset:27648
	ds_write_b128 v152, v[228:231] offset:45056
	ds_write_b128 v154, v[232:235] offset:27648
	ds_write_b128 v154, v[236:239] offset:45056
	ds_write_b128 v156, v[240:243] offset:27648
	ds_write_b128 v156, v[244:247] offset:45056
	ds_write_b128 v158, v[248:251] offset:27648
	ds_write_b128 v158, v[194:197] offset:45056
	s_branch .Lqkpf_join_10107
.Lqkpf_orig_10107:
	s_and_saveexec_b64 s[40:41], vcc
	s_cbranch_execz .Lqk_10107_0
	v_add_u32_e32 v2, s73, v189
	v_ashrrev_i32_e32 v3, 31, v2
	v_lshlrev_b64 v[2:3], 10, v[2:3]
	v_lshl_or_b32 v2, v172, 1, v2
	v_lshl_add_u64 v[70:71], s[96:97], 0, v[2:3]
	v_lshl_add_u64 v[2:3], s[94:95], 0, v[2:3]
	global_load_dwordx4 v[74:77], v[2:3], off
	s_nop 0
	global_load_dwordx4 v[70:73], v[70:71], off

.Lqkpf_join_10107:
	s_add_i32 s72, s72, 1
	s_cmp_ge_u32 s72, s50
	v_mov_b64_e32 v[70:71], v[62:63]
	v_mov_b64_e32 v[68:69], v[60:61]
	v_mov_b64_e32 v[74:75], v[58:59]
	v_mov_b64_e32 v[72:73], v[56:57]
	s_waitcnt lgkmcnt(0)
	s_barrier
	s_cbranch_scc1 .LBB0_684
	v_add_u32_e32 v252, s73, v189
	v_add_u32_e32 v252, 64, v252
	v_ashrrev_i32_e32 v253, 31, v252
	v_lshlrev_b64 v[252:253], 10, v[252:253]
	v_lshl_or_b32 v252, v172, 1, v252
	v_lshl_add_u64 v[228:229], s[96:97], 0, v[252:253]
	v_lshl_add_u64 v[252:253], s[94:95], 0, v[252:253]
	global_load_dwordx4 v[224:227], v[252:253], off
	s_nop 0
	global_load_dwordx4 v[228:231], v[228:229], off
	v_add_u32_e32 v252, s73, v153
	v_add_u32_e32 v252, 64, v252
	v_ashrrev_i32_e32 v253, 31, v252
	v_lshlrev_b64 v[252:253], 10, v[252:253]
	v_lshl_or_b32 v252, v172, 1, v252
	v_lshl_add_u64 v[236:237], s[96:97], 0, v[252:253]
	v_lshl_add_u64 v[252:253], s[94:95], 0, v[252:253]
	global_load_dwordx4 v[232:235], v[252:253], off
	s_nop 0
	global_load_dwordx4 v[236:239], v[236:237], off
	v_add_u32_e32 v252, s73, v155
	v_add_u32_e32 v252, 64, v252
	v_ashrrev_i32_e32 v253, 31, v252
	v_lshlrev_b64 v[252:253], 10, v[252:253]
	v_lshl_or_b32 v252, v172, 1, v252
	v_lshl_add_u64 v[244:245], s[96:97], 0, v[252:253]
	v_lshl_add_u64 v[252:253], s[94:95], 0, v[252:253]
	global_load_dwordx4 v[240:243], v[252:253], off
	s_nop 0
	global_load_dwordx4 v[244:247], v[244:245], off
	v_add_u32_e32 v252, s73, v157
	v_add_u32_e32 v252, 64, v252
	v_ashrrev_i32_e32 v253, 31, v252
	v_lshlrev_b64 v[252:253], 10, v[252:253]
	v_lshl_or_b32 v252, v172, 1, v252
	v_lshl_add_u64 v[194:195], s[96:97], 0, v[252:253]
	v_lshl_add_u64 v[252:253], s[94:95], 0, v[252:253]
	global_load_dwordx4 v[248:251], v[252:253], off
	s_nop 0
	global_load_dwordx4 v[194:197], v[194:195], off
	s_add_i32 s40, s42, 1
	s_cmpk_lt_i32 s42, 0xff
	s_cselect_b64 s[42:43], -1, 0
	s_ashr_i32 s41, s40, 31
	v_mov_b32_e32 v40, v0
	v_mov_b32_e32 v41, v0
	s_lshl_b64 s[44:45], s[40:41], 9
	v_mov_b32_e32 v42, v0
	v_mov_b32_e32 v43, v0
	v_mov_b64_e32 v[36:37], v[40:41]
	s_or_b64 s[42:43], s[42:43], s[4:5]
	s_or_b64 s[44:45], s[44:45], s[52:53]
	v_mov_b64_e32 v[38:39], v[42:43]
	s_and_saveexec_b64 s[48:49], s[42:43]
	s_cbranch_execz .LBB0_673
	v_lshl_add_u64 v[2:3], s[44:45], 0, v[144:145]
	v_lshlrev_b64 v[2:3], 7, v[2:3]
	v_lshl_add_u64 v[2:3], v[130:131], 0, v[2:3]
	global_load_dwordx4 v[36:39], v[2:3], off

.LBB0_1680:
	s_add_i32 s74, s72, s82
	s_cmpk_lt_i32 s74, 0x100
	s_cselect_b64 s[54:55], -1, 0
	s_and_b64 s[56:57], s[54:55], exec
	s_cselect_b32 s76, 64, 16
	s_barrier
	s_and_saveexec_b64 s[56:57], s[4:5]
	s_cbranch_execz .LBB0_1684
	v_cmp_gt_u32_e32 vcc, s76, v103
	v_mov_b32_e32 v2, 0
	s_and_saveexec_b64 s[58:59], vcc
	s_cbranch_execz .LBB0_1683
	s_cmp_eq_u32 s82, 0
	s_cbranch_scc1 .Lvw_1_a
	s_waitcnt vmcnt(20)
	s_branch .Lvw_1_b

.Lvw_1_b:
	v_add_f32_e32 v2, v226, v1
	s_mov_b32 s2, 0xbfb8aa3b
	v_mul_f32_e64 v3, |v2|, s2
	v_exp_f32_e32 v72, v3
	v_max_f32_e32 v73, 0, v2
	s_mov_b32 s2, 0x3f2aaaab
	v_add_f32_e32 v60, 1.0, v72
	v_add_f32_e32 v2, -1.0, v60
	v_sub_f32_e32 v3, v2, v60
	v_sub_f32_e32 v2, v72, v2
	v_add_f32_e32 v3, 1.0, v3
	v_frexp_mant_f32_e32 v61, v60
	v_add_f32_e32 v62, v2, v3
	v_cvt_f64_f32_e32 v[2:3], v60
	v_frexp_exp_i32_f64_e32 v2, v[2:3]
	v_cmp_gt_f32_e32 vcc, s2, v61
	s_mov_b32 s2, 0x3f317218
	s_nop 0
	v_subbrev_co_u32_e32 v66, vcc, 0, v2, vcc
	v_sub_u32_e32 v2, 0, v66
	v_ldexp_f32 v3, v60, v2
	v_ldexp_f32 v2, v62, v2
	v_add_f32_e32 v60, -1.0, v3
	v_add_f32_e32 v62, 1.0, v3
	v_add_f32_e32 v61, 1.0, v60
	v_add_f32_e32 v63, -1.0, v62
	v_sub_f32_e32 v61, v3, v61
	v_sub_f32_e32 v3, v3, v63
	v_add_f32_e32 v61, v2, v61
	v_add_f32_e32 v2, v2, v3
	v_add_f32_e32 v67, v62, v2
	v_rcp_f32_e32 v69, v67
	v_sub_f32_e32 v3, v67, v62
	v_sub_f32_e32 v68, v2, v3
	v_add_f32_e32 v3, v60, v61
	v_mul_f32_e32 v71, v3, v69
	v_sub_f32_e32 v2, v3, v60
	v_mul_f32_e32 v60, v67, v71
	v_fma_f32 v62, v71, v67, -v60
	v_fmac_f32_e32 v62, v71, v68
	v_sub_f32_e32 v70, v61, v2
	v_add_f32_e32 v2, v60, v62
	v_sub_f32_e32 v61, v3, v2
	v_pk_add_f32 v[64:65], v[2:3], v[60:61] neg_lo:[0,1] neg_hi:[0,1]
	v_mov_b32_e32 v63, v2
	v_pk_add_f32 v[2:3], v[64:65], v[62:63] neg_lo:[0,1] neg_hi:[0,1]
	s_nop 0
	v_add_f32_e32 v3, v70, v3
	v_add_f32_e32 v2, v2, v3
	v_add_f32_e32 v3, v61, v2
	v_mul_f32_e32 v70, v69, v3
	v_mul_f32_e32 v60, v67, v70
	v_fma_f32 v62, v70, v67, -v60
	v_fmac_f32_e32 v62, v70, v68
	v_sub_f32_e32 v61, v61, v3
	v_add_f32_e32 v67, v2, v61
	v_add_f32_e32 v2, v60, v62
	v_sub_f32_e32 v61, v3, v2
	v_pk_add_f32 v[64:65], v[2:3], v[60:61] neg_lo:[0,1] neg_hi:[0,1]
	v_mov_b32_e32 v63, v2
	v_pk_add_f32 v[2:3], v[64:65], v[62:63] neg_lo:[0,1] neg_hi:[0,1]
	s_nop 0
	v_add_f32_e32 v3, v67, v3
	v_add_f32_e32 v2, v2, v3
	v_add_f32_e32 v3, v71, v70
	v_add_f32_e32 v2, v61, v2
	v_sub_f32_e32 v60, v3, v71
	v_mul_f32_e32 v2, v69, v2
	v_sub_f32_e32 v60, v70, v60
	v_add_f32_e32 v60, v60, v2
	v_add_f32_e32 v62, v3, v60
	v_mul_f32_e32 v63, v62, v62
	v_fmamk_f32 v2, v63, 0x3e9b6dac, v212
	v_fmaak_f32 v139, v63, v2, 0x3f2aaada
	v_cvt_f32_i32_e32 v2, v66
	v_sub_f32_e32 v3, v62, v3
	v_sub_f32_e32 v3, v60, v3
	v_ldexp_f32 v64, v3, 1
	v_mul_f32_e32 v3, v62, v63
	v_ldexp_f32 v61, v62, 1
	v_pk_mul_f32 v[62:63], v[2:3], v[138:139]
	s_nop 0
	v_fma_f32 v60, v2, s2, -v62
	v_fmac_f32_e32 v60, 0xb102e308, v2
	v_pk_add_f32 v[2:3], v[62:63], v[60:61]
	s_mov_b32 s2, 0x7f800000
	v_sub_f32_e32 v61, v3, v61
	v_sub_f32_e32 v61, v63, v61
	v_add_f32_e32 v65, v64, v61
	v_mov_b32_e32 v64, v62
	v_pk_add_f32 v[62:63], v[2:3], v[62:63] neg_lo:[0,1] neg_hi:[0,1]
	v_pk_add_f32 v[66:67], v[2:3], v[64:65]
	v_mov_b32_e32 v61, v2
	v_mov_b32_e32 v63, v67
	v_pk_add_f32 v[68:69], v[60:61], v[62:63] neg_lo:[0,1] neg_hi:[0,1]
	v_pk_add_f32 v[60:61], v[60:61], v[62:63]
	v_mov_b32_e32 v64, v65
	v_pk_add_f32 v[62:63], v[60:61], v[2:3] op_sel:[1,0] op_sel_hi:[0,1] neg_lo:[0,1] neg_hi:[0,1]
	v_pk_add_f32 v[70:71], v[66:67], v[62:63] op_sel_hi:[1,0] neg_lo:[0,1] neg_hi:[0,1]
	v_mov_b32_e32 v66, v67
	v_mov_b32_e32 v67, v61
	v_pk_mov_b32 v[62:63], v[2:3], v[62:63] op_sel:[1,0]
	v_mov_b32_e32 v65, v2
	v_pk_add_f32 v[62:63], v[66:67], v[62:63] neg_lo:[0,1] neg_hi:[0,1]
	v_mov_b32_e32 v70, v68
	v_pk_add_f32 v[2:3], v[64:65], v[62:63] neg_lo:[0,1] neg_hi:[0,1]
	v_mov_b32_e32 v69, v61
	v_pk_add_f32 v[62:63], v[70:71], v[2:3]
	v_cmp_neq_f32_e32 vcc, s2, v72
	v_pk_add_f32 v[64:65], v[62:63], v[62:63] op_sel:[0,1] op_sel_hi:[1,0]
	s_mov_b32 s2, 0x33800000
	v_pk_add_f32 v[60:61], v[60:61], v[64:65] op_sel:[1,0] op_sel_hi:[0,1]
	v_mov_b32_e32 v63, v60
	v_pk_add_f32 v[66:67], v[62:63], v[68:69] neg_lo:[0,1] neg_hi:[0,1]
	v_mov_b32_e32 v3, v64
	v_sub_f32_e32 v61, v62, v66
	v_pk_add_f32 v[2:3], v[2:3], v[66:67] neg_lo:[0,1] neg_hi:[0,1]
	v_sub_f32_e32 v61, v68, v61
	v_add_f32_e32 v2, v2, v61
	v_add_f32_e32 v2, v2, v3
	v_add_f32_e32 v2, v60, v2
	v_cndmask_b32_e32 v2, v221, v2, vcc
	v_cmp_ngt_f32_e32 vcc, -1.0, v72
	s_nop 1
	v_cndmask_b32_e32 v2, v222, v2, vcc
	v_cmp_neq_f32_e32 vcc, -1.0, v72
	s_nop 1
	v_cndmask_b32_e32 v2, v223, v2, vcc
	v_cmp_lt_f32_e64 vcc, |v72|, s2
	s_nop 1
	v_cndmask_b32_e32 v2, v2, v72, vcc
	v_add_f32_e32 v2, v73, v2

.LBB0_1684:
	s_or_b64 exec, exec, s[56:57]
	s_add_i32 s2, s69, -16
	s_and_b64 s[54:55], s[54:55], exec
	s_cselect_b32 s77, s73, s2
	v_cmp_gt_i32_e32 vcc, s76, v165
	v_mov_b32_e32 v60, 0
	v_mov_b32_e32 v62, 0
	v_mov_b32_e32 v63, 0
	v_mov_b32_e32 v64, 0
	v_mov_b32_e32 v65, 0
	v_mov_b32_e32 v66, 0
	v_mov_b32_e32 v67, 0
	v_mov_b32_e32 v68, 0
	v_mov_b32_e32 v69, 0
	s_cmp_eq_u32 s82, 0
	s_cbranch_scc1 .Lvw_2_a
	s_waitcnt vmcnt(20)
	s_branch .Lvw_2_b

.Lvw_2_b:
	ds_write_b128 v197, v[36:39] offset:17408
	ds_write_b128 v201, v[40:43] offset:17408
	ds_write_b128 v213, v[44:47] offset:17408
	ds_write_b128 v214, v[48:51] offset:17408
	ds_write_b128 v197, v[52:55] offset:35840
	ds_write_b128 v201, v[56:59] offset:35840
	s_and_saveexec_b64 s[54:55], vcc
	s_cbranch_execz .Lcb_31495_0
	v_add_u32_e32 v2, s77, v165
	v_ashrrev_i32_e32 v3, 31, v2
	v_lshlrev_b64 v[2:3], 10, v[2:3]
	v_lshl_or_b32 v2, v150, 1, v2
	v_lshl_add_u64 v[62:63], s[80:81], 0, v[2:3]
	v_lshl_add_u64 v[2:3], s[88:89], 0, v[2:3]
	global_load_dwordx4 v[66:69], v[62:63], off
	s_nop 0
	global_load_dwordx4 v[62:65], v[2:3], off

.LBB0_2402:
	s_add_i32 s44, s2, s58
	s_cmpk_lt_i32 s44, 0x100
	s_cselect_b32 s60, 64, 16
	s_cselect_b32 s59, s55, s54
	v_cmp_gt_i32_e32 vcc, s60, v189
	v_mov_b32_e32 v68, 0
	v_mov_b32_e32 v70, 0
	v_mov_b32_e32 v71, 0
	v_mov_b32_e32 v72, 0
	v_mov_b32_e32 v73, 0
	v_mov_b32_e32 v74, 0
	v_mov_b32_e32 v75, 0
	v_mov_b32_e32 v76, 0
	v_mov_b32_e32 v77, 0
	s_waitcnt vmcnt(63) expcnt(7) lgkmcnt(15)
	s_barrier
	s_cmp_eq_u32 s58, 0
	s_cbranch_scc1 .Lgw_1_a
	s_waitcnt vmcnt(20)
	s_branch .Lgw_1_b

.Lgw_1_b:
	ds_write_b128 v198, v[36:39]
	ds_write_b128 v199, v[40:43]
	ds_write_b128 v200, v[44:47]
	ds_write_b128 v201, v[48:51]
	ds_write_b128 v198, v[52:55] offset:18432
	ds_write_b128 v199, v[64:67] offset:18432
	s_cmp_eq_u32 s58, 0
	s_cbranch_scc1 .Lqkpf_orig_43407
	ds_write_b128 v152, v[224:227] offset:27648
	ds_write_b128 v152, v[228:231] offset:45056
	ds_write_b128 v154, v[232:235] offset:27648
	ds_write_b128 v154, v[236:239] offset:45056
	ds_write_b128 v156, v[240:243] offset:27648
	ds_write_b128 v156, v[244:247] offset:45056
	ds_write_b128 v158, v[248:251] offset:27648
	ds_write_b128 v158, v[194:197] offset:45056
	s_branch .Lqkpf_join_43407
.Lqkpf_orig_43407:
	s_and_saveexec_b64 s[42:43], vcc
	s_cbranch_execz .Lqk_43407_0
	v_add_u32_e32 v2, s59, v189
	v_ashrrev_i32_e32 v3, 31, v2
	v_lshlrev_b64 v[2:3], 10, v[2:3]
	v_lshl_or_b32 v2, v172, 1, v2
	v_lshl_add_u64 v[70:71], s[96:97], 0, v[2:3]
	v_lshl_add_u64 v[2:3], s[94:95], 0, v[2:3]
	global_load_dwordx4 v[74:77], v[2:3], off
	s_nop 0
	global_load_dwordx4 v[70:73], v[70:71], off

.Lqkpf_join_43407:
	s_add_i32 s58, s58, 1
	s_cmp_ge_u32 s58, s3
	v_mov_b64_e32 v[70:71], v[62:63]
	v_mov_b64_e32 v[68:69], v[60:61]
	v_mov_b64_e32 v[74:75], v[58:59]
	v_mov_b64_e32 v[72:73], v[56:57]
	s_waitcnt lgkmcnt(0)
	s_barrier
	s_cbranch_scc1 .LBB0_2424
	v_add_u32_e32 v252, s59, v189
	v_add_u32_e32 v252, 64, v252
	v_ashrrev_i32_e32 v253, 31, v252
	v_lshlrev_b64 v[252:253], 10, v[252:253]
	v_lshl_or_b32 v252, v172, 1, v252
	v_lshl_add_u64 v[228:229], s[96:97], 0, v[252:253]
	v_lshl_add_u64 v[252:253], s[94:95], 0, v[252:253]
	global_load_dwordx4 v[224:227], v[252:253], off
	s_nop 0
	global_load_dwordx4 v[228:231], v[228:229], off
	v_add_u32_e32 v252, s59, v153
	v_add_u32_e32 v252, 64, v252
	v_ashrrev_i32_e32 v253, 31, v252
	v_lshlrev_b64 v[252:253], 10, v[252:253]
	v_lshl_or_b32 v252, v172, 1, v252
	v_lshl_add_u64 v[236:237], s[96:97], 0, v[252:253]
	v_lshl_add_u64 v[252:253], s[94:95], 0, v[252:253]
	global_load_dwordx4 v[232:235], v[252:253], off
	s_nop 0
	global_load_dwordx4 v[236:239], v[236:237], off
	v_add_u32_e32 v252, s59, v155
	v_add_u32_e32 v252, 64, v252
	v_ashrrev_i32_e32 v253, 31, v252
	v_lshlrev_b64 v[252:253], 10, v[252:253]
	v_lshl_or_b32 v252, v172, 1, v252
	v_lshl_add_u64 v[244:245], s[96:97], 0, v[252:253]
	v_lshl_add_u64 v[252:253], s[94:95], 0, v[252:253]
	global_load_dwordx4 v[240:243], v[252:253], off
	s_nop 0
	global_load_dwordx4 v[244:247], v[244:245], off
	v_add_u32_e32 v252, s59, v157
	v_add_u32_e32 v252, 64, v252
	v_ashrrev_i32_e32 v253, 31, v252
	v_lshlrev_b64 v[252:253], 10, v[252:253]
	v_lshl_or_b32 v252, v172, 1, v252
	v_lshl_add_u64 v[194:195], s[96:97], 0, v[252:253]
	v_lshl_add_u64 v[252:253], s[94:95], 0, v[252:253]
	global_load_dwordx4 v[248:251], v[252:253], off
	s_nop 0
	global_load_dwordx4 v[194:197], v[194:195], off
	s_add_i32 s42, s44, 1
	s_cmpk_lt_i32 s44, 0xff
	s_cselect_b64 s[44:45], -1, 0
	s_ashr_i32 s43, s42, 31
	v_mov_b32_e32 v40, v0
	v_mov_b32_e32 v41, v0
	s_lshl_b64 s[46:47], s[42:43], 9
	v_mov_b32_e32 v42, v0
	v_mov_b32_e32 v43, v0
	v_mov_b64_e32 v[36:37], v[40:41]
	s_or_b64 s[44:45], s[44:45], s[6:7]
	s_or_b64 s[46:47], s[46:47], s[0:1]
	v_mov_b64_e32 v[38:39], v[42:43]
	s_and_saveexec_b64 s[52:53], s[44:45]
	s_cbranch_execz .LBB0_2413
	v_lshl_add_u64 v[2:3], s[46:47], 0, v[144:145]
	v_lshlrev_b64 v[2:3], 7, v[2:3]
	v_lshl_add_u64 v[2:3], v[130:131], 0, v[2:3]
	global_load_dwordx4 v[36:39], v[2:3], off
